# hand-scheduled RWKV scan loop: software-pipelined LDS reads, hazard slots filled, same f32 math
# speedup vs baseline: 1.0315x; 1.0315x over previous
.LBB0_1063:
	s_andn2_b64 vcc, exec, s[0:1]
	s_cbranch_vccnz .LBB0_1071
	v_readlane_b32 s0, v207, 5
	v_readlane_b32 s1, v207, 6
	s_and_b64 s[0:1], s[0:1], exec
	v_readlane_b32 s0, v208, 26
	s_cselect_b32 s0, s0, s97
	s_and_b32 s7, s0, 3
	s_lshr_b32 s6, s0, 2
	s_lshr_b32 s9, s0, 5
	s_lshl_b32 s2, s6, 5
	s_and_b32 s2, s2, 0xc0
	s_and_b32 s3, s6, 1
	v_readlane_b32 s4, v210, 50
	v_readlane_b32 s5, v210, 51
	v_readlane_b32 s52, v210, 32
	v_readlane_b32 s53, v210, 33
	v_readlane_b32 s8, v208, 60
	s_cmp_eq_u32 s3, 0
	s_cselect_b32 s46, s14, s16
	s_cselect_b32 s47, s15, s17
	s_cselect_b32 s48, s18, s20
	s_cselect_b32 s49, s19, s21
	s_cselect_b32 s50, s26, s4
	s_cselect_b32 s51, s27, s5
	s_cselect_b32 s34, 16, -16
	s_cselect_b32 s10, 1, -1
	s_cselect_b32 s54, 0, 0xff
	s_cselect_b32 s55, 0, 0xfff
	s_lshl_b32 s0, s9, 8
	s_add_i32 s0, s0, 0x4000
	s_add_i32 s54, s54, s0
	s_lshl_b32 s0, s9, 12
	s_add_i32 s55, s55, s0
	s_setprio 3
	v_lshrrev_b32_e32 v119, 4, v133
	v_and_b32_e32 v120, 15, v133
	v_and_b32_e32 v121, 12, v120
	v_and_b32_e32 v0, 1, v120
	v_lshl_or_b32 v121, v0, 1, v121
	v_bfe_u32 v0, v120, 1, 1
	v_or_b32_e32 v121, v121, v0
	v_mul_i32_i24_e32 v0, s10, v119
	v_add_u32_e32 v113, s54, v0
	v_add_u32_e32 v117, s55, v0
	v_mul_i32_i24_e32 v0, s10, v121
	v_add_u32_e32 v114, s54, v0
	v_add_u32_e32 v126, s55, v0
	v_and_b32_e32 v0, 8, v120
	v_cmp_ne_u32_e64 s[38:39], 0, v0
	v_and_b32_e32 v0, 4, v120
	v_cmp_ne_u32_e64 s[40:41], 0, v0
	v_and_b32_e32 v0, 1, v120
	v_cmp_ne_u32_e64 s[42:43], 0, v0
	v_and_b32_e32 v0, 2, v120
	v_cmp_ne_u32_e64 s[44:45], 0, v0
	v_lshlrev_b32_e32 v0, 4, v120
	s_lshl_b32 s0, s2, 2
	v_add_u32_e32 v115, s0, v0
	s_lshl_b32 s1, s7, 4
	v_add_u32_e32 v122, s1, v119
	v_lshl_add_u32 v116, v122, 2, s0
	v_mov_b32_e32 v110, v0
	v_lshlrev_b32_e32 v111, 2, v122
	v_lshl_add_u32 v112, v119, 8, v0
	s_lshl_b32 s8, s8, 10
	s_add_u32 s52, s52, s8
	s_addc_u32 s53, s53, 0
	global_load_dwordx4 v[6:9], v115, s[52:53]
	v_mov_b32_e32 v2, 0
	v_mov_b32_e32 v3, 0
	v_mov_b32_e32 v4, 0
	v_mov_b32_e32 v5, 0
	v_mov_b32_e32 v82, 0
	v_mov_b32_e32 v83, 0
	v_mov_b32_e32 v84, 0
	v_mov_b32_e32 v85, 0
	v_mov_b32_e32 v92, 0
	s_mov_b32 s33, 0
	v_mul_u32_u24_e32 v0, 0xf00, v113
	v_lshl_add_u32 v125, v113, 10, v115
	v_add_u32_e32 v0, v0, v115
	v_add_u32_e32 v113, s34, v113
	global_load_dwordx4 v[22:25], v125, s[46:47]
	global_load_dwordx4 v[26:29], v125, s[48:49]
	global_load_dwordx4 v[30:33], v125, s[22:23]
	global_load_dwordx4 v[14:17], v0, s[12:13] offset:1024
	global_load_dwordx4 v[10:13], v0, s[12:13]
	global_load_dwordx4 v[18:21], v0, s[12:13] offset:2048
	s_waitcnt vmcnt(0)
	v_pk_add_f32 v[122:123], v[26:27], -1.0 op_sel_hi:[1,0]
	v_pk_add_f32 v[124:125], v[28:29], -1.0 op_sel_hi:[1,0]
	v_pk_mul_f32 v[118:119], v[30:31], v[26:27]
	v_pk_fma_f32 v[122:123], v[6:7], v[122:123], 1.0 op_sel_hi:[1,1,0]
	v_pk_fma_f32 v[124:125], v[8:9], v[124:125], 1.0 op_sel_hi:[1,1,0]
	v_pk_mul_f32 v[120:121], v[32:33], v[28:29]
	v_pk_mul_f32 v[122:123], v[14:15], v[122:123]
	v_pk_mul_f32 v[124:125], v[16:17], v[124:125]
	ds_write_b128 v112, v[22:25] offset:0
	ds_write_b128 v112, v[30:33] offset:4096
	ds_write_b128 v112, v[10:13] offset:16384
	ds_write_b128 v112, v[18:21] offset:20480
	ds_write_b128 v112, v[118:121] offset:8192
	ds_write_b128 v112, v[122:125] offset:12288
	s_waitcnt lgkmcnt(0)
	v_xor_b32_e32 v112, 0x6000, v112
	s_barrier
.Lscan_chunk:
	ds_read_b128 v[38:41], v110 offset:4096
	ds_read_b128 v[34:37], v110 offset:0
	ds_read_b128 v[46:49], v110 offset:12288
	ds_read_b32 v54, v111 offset:20480
	ds_read_b128 v[42:45], v110 offset:8192
	ds_read_b128 v[50:53], v110 offset:16384
	ds_read_b128 v[60:63], v110 offset:4352
	ds_read_b128 v[56:59], v110 offset:256
	ds_read_b128 v[68:71], v110 offset:12544
	ds_read_b32 v76, v111 offset:20736
	ds_read_b128 v[64:67], v110 offset:8448
	ds_read_b128 v[72:75], v110 offset:16640
	s_cmpk_eq_i32 s33, 0x10f
	s_cbranch_scc1 .Lscan_nogload
	v_mul_u32_u24_e32 v0, 0xf00, v113
	v_lshl_add_u32 v125, v113, 10, v115
	v_add_u32_e32 v0, v0, v115
	v_add_u32_e32 v113, s34, v113
	global_load_dwordx4 v[22:25], v125, s[46:47]
	global_load_dwordx4 v[26:29], v125, s[48:49]
	global_load_dwordx4 v[30:33], v125, s[22:23]
	global_load_dwordx4 v[14:17], v0, s[12:13] offset:1024
	global_load_dwordx4 v[10:13], v0, s[12:13]
	global_load_dwordx4 v[18:21], v0, s[12:13] offset:2048
	s_cmp_eq_u32 s33, 14
	s_cbranch_scc0 .Lscan_nogload
	v_mov_b32_e32 v113, v117
.Lscan_nogload:
	s_cmp_eq_u32 s33, 0
	s_cbranch_scc1 .Lscan_nored
	v_cndmask_b32_e64 v118, v102, v94, s[38:39]
	v_cndmask_b32_e64 v119, v103, v95, s[38:39]
	v_cndmask_b32_e64 v120, v104, v96, s[38:39]
	v_cndmask_b32_e64 v121, v105, v97, s[38:39]
	v_cndmask_b32_e64 v122, v106, v98, s[38:39]
	v_cndmask_b32_e64 v123, v107, v99, s[38:39]
	v_cndmask_b32_e64 v124, v108, v100, s[38:39]
	v_cndmask_b32_e64 v125, v109, v101, s[38:39]
	v_cndmask_b32_e64 v94, v94, v102, s[38:39]
	v_cndmask_b32_e64 v95, v95, v103, s[38:39]
	v_cndmask_b32_e64 v96, v96, v104, s[38:39]
	v_cndmask_b32_e64 v97, v97, v105, s[38:39]
	v_cndmask_b32_e64 v98, v98, v106, s[38:39]
	v_cndmask_b32_e64 v99, v99, v107, s[38:39]
	v_cndmask_b32_e64 v100, v100, v108, s[38:39]
	v_cndmask_b32_e64 v101, v101, v109, s[38:39]
	v_add_f32_dpp v94, v118, v94 row_ror:8 row_mask:0xf bank_mask:0xf bound_ctrl:1
	v_add_f32_dpp v95, v119, v95 row_ror:8 row_mask:0xf bank_mask:0xf bound_ctrl:1
	v_add_f32_dpp v96, v120, v96 row_ror:8 row_mask:0xf bank_mask:0xf bound_ctrl:1
	v_add_f32_dpp v97, v121, v97 row_ror:8 row_mask:0xf bank_mask:0xf bound_ctrl:1
	v_add_f32_dpp v98, v122, v98 row_ror:8 row_mask:0xf bank_mask:0xf bound_ctrl:1
	v_add_f32_dpp v99, v123, v99 row_ror:8 row_mask:0xf bank_mask:0xf bound_ctrl:1
	v_add_f32_dpp v100, v124, v100 row_ror:8 row_mask:0xf bank_mask:0xf bound_ctrl:1
	v_add_f32_dpp v101, v125, v101 row_ror:8 row_mask:0xf bank_mask:0xf bound_ctrl:1
	v_cndmask_b32_e64 v118, v98, v94, s[40:41]
	v_cndmask_b32_e64 v119, v99, v95, s[40:41]
	v_cndmask_b32_e64 v120, v100, v96, s[40:41]
	v_cndmask_b32_e64 v121, v101, v97, s[40:41]
	v_cndmask_b32_e64 v94, v94, v98, s[40:41]
	v_cndmask_b32_e64 v95, v95, v99, s[40:41]
	v_cndmask_b32_e64 v96, v96, v100, s[40:41]
	v_cndmask_b32_e64 v97, v97, v101, s[40:41]
	v_add_f32_dpp v94, v118, v94 row_half_mirror row_mask:0xf bank_mask:0xf bound_ctrl:1
	v_add_f32_dpp v95, v119, v95 row_half_mirror row_mask:0xf bank_mask:0xf bound_ctrl:1
	v_add_f32_dpp v96, v120, v96 row_half_mirror row_mask:0xf bank_mask:0xf bound_ctrl:1
	v_add_f32_dpp v97, v121, v97 row_half_mirror row_mask:0xf bank_mask:0xf bound_ctrl:1
	v_cndmask_b32_e64 v118, v96, v94, s[42:43]
	v_cndmask_b32_e64 v119, v97, v95, s[42:43]
	v_cndmask_b32_e64 v94, v94, v96, s[42:43]
	v_cndmask_b32_e64 v95, v95, v97, s[42:43]
	s_nop 0
	v_add_f32_dpp v94, v118, v94 quad_perm:[1,0,3,2] row_mask:0xf bank_mask:0xf bound_ctrl:1
	v_add_f32_dpp v95, v119, v95 quad_perm:[1,0,3,2] row_mask:0xf bank_mask:0xf bound_ctrl:1
	s_nop 0
	v_cndmask_b32_e64 v118, v95, v94, s[44:45]
	v_cndmask_b32_e64 v94, v94, v95, s[44:45]
	s_nop 1
	v_add_f32_dpp v94, v118, v94 quad_perm:[2,3,0,1] row_mask:0xf bank_mask:0xf bound_ctrl:1
	v_lshl_add_u32 v0, v114, 10, v116
	v_add_u32_e32 v114, s34, v114
	global_store_dword v0, v94, s[50:51]
	s_cmp_eq_u32 s33, 16
	s_cbranch_scc0 .Lscan_nored
	v_mov_b32_e32 v114, v126
.Lscan_nored:
	s_waitcnt lgkmcnt(11)
	v_pk_mul_f32 v[86:87], v[2:3], v[38:39]
	s_waitcnt lgkmcnt(10)
	v_pk_mul_f32 v[78:79], v[2:3], v[34:35]
	v_pk_fma_f32 v[86:87], v[4:5], v[40:41], v[86:87]
	v_pk_mul_f32 v[80:81], v[4:5], v[36:37]
	ds_read_b128 v[38:41], v110 offset:4608
	v_add_f32_e32 v90, v86, v87
	s_waitcnt lgkmcnt(9)
	v_pk_fma_f32 v[82:83], v[54:55], v[46:47], v[78:79] op_sel_hi:[0,1,1]
	ds_read_b128 v[34:37], v110 offset:512
	v_add_f32_dpp v90, v90, v90 quad_perm:[1,0,3,2] row_mask:0xf bank_mask:0xf bound_ctrl:1
	v_pk_fma_f32 v[84:85], v[54:55], v[48:49], v[80:81] op_sel_hi:[0,1,1]
	ds_read_b128 v[46:49], v110 offset:12800
	v_add_f32_dpp v90, v90, v90 quad_perm:[2,3,0,1] row_mask:0xf bank_mask:0xf bound_ctrl:1
	ds_read_b32 v54, v111 offset:20992
	s_nop 0
	v_add_f32_dpp v90, v90, v90 row_half_mirror row_mask:0xf bank_mask:0xf bound_ctrl:1
	s_nop 0
	s_nop 0
	v_add_f32_dpp v92, v90, v90 row_mirror row_mask:0xf bank_mask:0xf bound_ctrl:1
	s_waitcnt lgkmcnt(11)
	v_pk_fma_f32 v[2:3], v[92:93], v[42:43], v[82:83] op_sel_hi:[0,1,1] neg_lo:[1,0,0] neg_hi:[1,0,0]
	v_pk_fma_f32 v[4:5], v[92:93], v[44:45], v[84:85] op_sel_hi:[0,1,1] neg_lo:[1,0,0] neg_hi:[1,0,0]
	ds_read_b128 v[42:45], v110 offset:8704
	s_waitcnt lgkmcnt(10)
	v_pk_mul_f32 v[86:87], v[2:3], v[60:61]
	s_waitcnt lgkmcnt(9)
	v_pk_mul_f32 v[78:79], v[2:3], v[56:57]
	v_pk_fma_f32 v[86:87], v[4:5], v[62:63], v[86:87]
	v_pk_mul_f32 v[80:81], v[4:5], v[58:59]
	v_pk_mul_f32 v[88:89], v[2:3], v[50:51]
	v_add_f32_e32 v90, v86, v87
	s_waitcnt lgkmcnt(7)
	v_pk_fma_f32 v[82:83], v[76:77], v[68:69], v[78:79] op_sel_hi:[0,1,1]
	v_pk_fma_f32 v[88:89], v[4:5], v[52:53], v[88:89]
	v_add_f32_dpp v90, v90, v90 quad_perm:[1,0,3,2] row_mask:0xf bank_mask:0xf bound_ctrl:1
	v_pk_fma_f32 v[84:85], v[76:77], v[70:71], v[80:81] op_sel_hi:[0,1,1]
	ds_read_b128 v[60:63], v110 offset:4864
	v_add_f32_dpp v90, v90, v90 quad_perm:[2,3,0,1] row_mask:0xf bank_mask:0xf bound_ctrl:1
	ds_read_b128 v[56:59], v110 offset:768
	v_add_f32_e32 v94, v88, v89
	v_add_f32_dpp v90, v90, v90 row_half_mirror row_mask:0xf bank_mask:0xf bound_ctrl:1
	ds_read_b128 v[50:53], v110 offset:16896
	ds_read_b128 v[68:71], v110 offset:13056
	v_add_f32_dpp v92, v90, v90 row_mirror row_mask:0xf bank_mask:0xf bound_ctrl:1
	ds_read_b32 v76, v111 offset:21248
	s_waitcnt lgkmcnt(11)
	v_pk_fma_f32 v[2:3], v[92:93], v[64:65], v[82:83] op_sel_hi:[0,1,1] neg_lo:[1,0,0] neg_hi:[1,0,0]
	v_pk_fma_f32 v[4:5], v[92:93], v[66:67], v[84:85] op_sel_hi:[0,1,1] neg_lo:[1,0,0] neg_hi:[1,0,0]
	ds_read_b128 v[64:67], v110 offset:8960
	s_waitcnt lgkmcnt(10)
	v_pk_mul_f32 v[86:87], v[2:3], v[38:39]
	s_waitcnt lgkmcnt(9)
	v_pk_mul_f32 v[78:79], v[2:3], v[34:35]
	v_pk_fma_f32 v[86:87], v[4:5], v[40:41], v[86:87]
	v_pk_mul_f32 v[80:81], v[4:5], v[36:37]
	v_pk_mul_f32 v[88:89], v[2:3], v[72:73]
	v_add_f32_e32 v90, v86, v87
	s_waitcnt lgkmcnt(7)
	v_pk_fma_f32 v[82:83], v[54:55], v[46:47], v[78:79] op_sel_hi:[0,1,1]
	v_pk_fma_f32 v[88:89], v[4:5], v[74:75], v[88:89]
	v_add_f32_dpp v90, v90, v90 quad_perm:[1,0,3,2] row_mask:0xf bank_mask:0xf bound_ctrl:1
	v_pk_fma_f32 v[84:85], v[54:55], v[48:49], v[80:81] op_sel_hi:[0,1,1]
	ds_read_b128 v[38:41], v110 offset:5120
	v_add_f32_dpp v90, v90, v90 quad_perm:[2,3,0,1] row_mask:0xf bank_mask:0xf bound_ctrl:1
	ds_read_b128 v[34:37], v110 offset:1024
	v_add_f32_e32 v95, v88, v89
	v_add_f32_dpp v90, v90, v90 row_half_mirror row_mask:0xf bank_mask:0xf bound_ctrl:1
	ds_read_b128 v[72:75], v110 offset:17152
	ds_read_b128 v[46:49], v110 offset:13312
	v_add_f32_dpp v92, v90, v90 row_mirror row_mask:0xf bank_mask:0xf bound_ctrl:1
	ds_read_b32 v54, v111 offset:21504
	s_waitcnt lgkmcnt(11)
	v_pk_fma_f32 v[2:3], v[92:93], v[42:43], v[82:83] op_sel_hi:[0,1,1] neg_lo:[1,0,0] neg_hi:[1,0,0]
	v_pk_fma_f32 v[4:5], v[92:93], v[44:45], v[84:85] op_sel_hi:[0,1,1] neg_lo:[1,0,0] neg_hi:[1,0,0]
	ds_read_b128 v[42:45], v110 offset:9216
	s_waitcnt lgkmcnt(11)
	v_pk_mul_f32 v[86:87], v[2:3], v[60:61]
	s_waitcnt lgkmcnt(10)
	v_pk_mul_f32 v[78:79], v[2:3], v[56:57]
	v_pk_fma_f32 v[86:87], v[4:5], v[62:63], v[86:87]
	v_pk_mul_f32 v[80:81], v[4:5], v[58:59]
	s_waitcnt lgkmcnt(9)
	v_pk_mul_f32 v[88:89], v[2:3], v[50:51]
	v_add_f32_e32 v90, v86, v87
	s_waitcnt lgkmcnt(7)
	v_pk_fma_f32 v[82:83], v[76:77], v[68:69], v[78:79] op_sel_hi:[0,1,1]
	v_pk_fma_f32 v[88:89], v[4:5], v[52:53], v[88:89]
	v_add_f32_dpp v90, v90, v90 quad_perm:[1,0,3,2] row_mask:0xf bank_mask:0xf bound_ctrl:1
	v_pk_fma_f32 v[84:85], v[76:77], v[70:71], v[80:81] op_sel_hi:[0,1,1]
	ds_read_b128 v[60:63], v110 offset:5376
	v_add_f32_dpp v90, v90, v90 quad_perm:[2,3,0,1] row_mask:0xf bank_mask:0xf bound_ctrl:1
	ds_read_b128 v[56:59], v110 offset:1280
	v_add_f32_e32 v96, v88, v89
	v_add_f32_dpp v90, v90, v90 row_half_mirror row_mask:0xf bank_mask:0xf bound_ctrl:1
	ds_read_b128 v[50:53], v110 offset:17408
	ds_read_b128 v[68:71], v110 offset:13568
	v_add_f32_dpp v92, v90, v90 row_mirror row_mask:0xf bank_mask:0xf bound_ctrl:1
	ds_read_b32 v76, v111 offset:21760
	s_waitcnt lgkmcnt(11)
	v_pk_fma_f32 v[2:3], v[92:93], v[64:65], v[82:83] op_sel_hi:[0,1,1] neg_lo:[1,0,0] neg_hi:[1,0,0]
	v_pk_fma_f32 v[4:5], v[92:93], v[66:67], v[84:85] op_sel_hi:[0,1,1] neg_lo:[1,0,0] neg_hi:[1,0,0]
	ds_read_b128 v[64:67], v110 offset:9472
	s_waitcnt lgkmcnt(11)
	v_pk_mul_f32 v[86:87], v[2:3], v[38:39]
	s_waitcnt lgkmcnt(10)
	v_pk_mul_f32 v[78:79], v[2:3], v[34:35]
	v_pk_fma_f32 v[86:87], v[4:5], v[40:41], v[86:87]
	v_pk_mul_f32 v[80:81], v[4:5], v[36:37]
	s_waitcnt lgkmcnt(9)
	v_pk_mul_f32 v[88:89], v[2:3], v[72:73]
	v_add_f32_e32 v90, v86, v87
	s_waitcnt lgkmcnt(7)
	v_pk_fma_f32 v[82:83], v[54:55], v[46:47], v[78:79] op_sel_hi:[0,1,1]
	v_pk_fma_f32 v[88:89], v[4:5], v[74:75], v[88:89]
	v_add_f32_dpp v90, v90, v90 quad_perm:[1,0,3,2] row_mask:0xf bank_mask:0xf bound_ctrl:1
	v_pk_fma_f32 v[84:85], v[54:55], v[48:49], v[80:81] op_sel_hi:[0,1,1]
	ds_read_b128 v[38:41], v110 offset:5632
	v_add_f32_dpp v90, v90, v90 quad_perm:[2,3,0,1] row_mask:0xf bank_mask:0xf bound_ctrl:1
	ds_read_b128 v[34:37], v110 offset:1536
	v_add_f32_e32 v97, v88, v89
	v_add_f32_dpp v90, v90, v90 row_half_mirror row_mask:0xf bank_mask:0xf bound_ctrl:1
	ds_read_b128 v[72:75], v110 offset:17664
	ds_read_b128 v[46:49], v110 offset:13824
	v_add_f32_dpp v92, v90, v90 row_mirror row_mask:0xf bank_mask:0xf bound_ctrl:1
	ds_read_b32 v54, v111 offset:22016
	s_waitcnt lgkmcnt(11)
	v_pk_fma_f32 v[2:3], v[92:93], v[42:43], v[82:83] op_sel_hi:[0,1,1] neg_lo:[1,0,0] neg_hi:[1,0,0]
	v_pk_fma_f32 v[4:5], v[92:93], v[44:45], v[84:85] op_sel_hi:[0,1,1] neg_lo:[1,0,0] neg_hi:[1,0,0]
	ds_read_b128 v[42:45], v110 offset:9728
	s_waitcnt lgkmcnt(11)
	v_pk_mul_f32 v[86:87], v[2:3], v[60:61]
	s_waitcnt lgkmcnt(10)
	v_pk_mul_f32 v[78:79], v[2:3], v[56:57]
	v_pk_fma_f32 v[86:87], v[4:5], v[62:63], v[86:87]
	v_pk_mul_f32 v[80:81], v[4:5], v[58:59]
	s_waitcnt lgkmcnt(9)
	v_pk_mul_f32 v[88:89], v[2:3], v[50:51]
	v_add_f32_e32 v90, v86, v87
	s_waitcnt lgkmcnt(7)
	v_pk_fma_f32 v[82:83], v[76:77], v[68:69], v[78:79] op_sel_hi:[0,1,1]
	v_pk_fma_f32 v[88:89], v[4:5], v[52:53], v[88:89]
	v_add_f32_dpp v90, v90, v90 quad_perm:[1,0,3,2] row_mask:0xf bank_mask:0xf bound_ctrl:1
	v_pk_fma_f32 v[84:85], v[76:77], v[70:71], v[80:81] op_sel_hi:[0,1,1]
	ds_read_b128 v[60:63], v110 offset:5888
	v_add_f32_dpp v90, v90, v90 quad_perm:[2,3,0,1] row_mask:0xf bank_mask:0xf bound_ctrl:1
	ds_read_b128 v[56:59], v110 offset:1792
	v_add_f32_e32 v98, v88, v89
	v_add_f32_dpp v90, v90, v90 row_half_mirror row_mask:0xf bank_mask:0xf bound_ctrl:1
	ds_read_b128 v[50:53], v110 offset:17920
	ds_read_b128 v[68:71], v110 offset:14080
	v_add_f32_dpp v92, v90, v90 row_mirror row_mask:0xf bank_mask:0xf bound_ctrl:1
	ds_read_b32 v76, v111 offset:22272
	s_waitcnt lgkmcnt(11)
	v_pk_fma_f32 v[2:3], v[92:93], v[64:65], v[82:83] op_sel_hi:[0,1,1] neg_lo:[1,0,0] neg_hi:[1,0,0]
	v_pk_fma_f32 v[4:5], v[92:93], v[66:67], v[84:85] op_sel_hi:[0,1,1] neg_lo:[1,0,0] neg_hi:[1,0,0]
	ds_read_b128 v[64:67], v110 offset:9984
	s_waitcnt lgkmcnt(11)
	v_pk_mul_f32 v[86:87], v[2:3], v[38:39]
	s_waitcnt lgkmcnt(10)
	v_pk_mul_f32 v[78:79], v[2:3], v[34:35]
	v_pk_fma_f32 v[86:87], v[4:5], v[40:41], v[86:87]
	v_pk_mul_f32 v[80:81], v[4:5], v[36:37]
	s_waitcnt lgkmcnt(9)
	v_pk_mul_f32 v[88:89], v[2:3], v[72:73]
	v_add_f32_e32 v90, v86, v87
	s_waitcnt lgkmcnt(7)
	v_pk_fma_f32 v[82:83], v[54:55], v[46:47], v[78:79] op_sel_hi:[0,1,1]
	v_pk_fma_f32 v[88:89], v[4:5], v[74:75], v[88:89]
	v_add_f32_dpp v90, v90, v90 quad_perm:[1,0,3,2] row_mask:0xf bank_mask:0xf bound_ctrl:1
	v_pk_fma_f32 v[84:85], v[54:55], v[48:49], v[80:81] op_sel_hi:[0,1,1]
	ds_read_b128 v[38:41], v110 offset:6144
	v_add_f32_dpp v90, v90, v90 quad_perm:[2,3,0,1] row_mask:0xf bank_mask:0xf bound_ctrl:1
	ds_read_b128 v[34:37], v110 offset:2048
	v_add_f32_e32 v99, v88, v89
	v_add_f32_dpp v90, v90, v90 row_half_mirror row_mask:0xf bank_mask:0xf bound_ctrl:1
	ds_read_b128 v[72:75], v110 offset:18176
	ds_read_b128 v[46:49], v110 offset:14336
	v_add_f32_dpp v92, v90, v90 row_mirror row_mask:0xf bank_mask:0xf bound_ctrl:1
	ds_read_b32 v54, v111 offset:22528
	s_waitcnt lgkmcnt(11)
	v_pk_fma_f32 v[2:3], v[92:93], v[42:43], v[82:83] op_sel_hi:[0,1,1] neg_lo:[1,0,0] neg_hi:[1,0,0]
	v_pk_fma_f32 v[4:5], v[92:93], v[44:45], v[84:85] op_sel_hi:[0,1,1] neg_lo:[1,0,0] neg_hi:[1,0,0]
	ds_read_b128 v[42:45], v110 offset:10240
	s_waitcnt lgkmcnt(11)
	v_pk_mul_f32 v[86:87], v[2:3], v[60:61]
	s_waitcnt lgkmcnt(10)
	v_pk_mul_f32 v[78:79], v[2:3], v[56:57]
	v_pk_fma_f32 v[86:87], v[4:5], v[62:63], v[86:87]
	v_pk_mul_f32 v[80:81], v[4:5], v[58:59]
	s_waitcnt lgkmcnt(9)
	v_pk_mul_f32 v[88:89], v[2:3], v[50:51]
	v_add_f32_e32 v90, v86, v87
	s_waitcnt lgkmcnt(7)
	v_pk_fma_f32 v[82:83], v[76:77], v[68:69], v[78:79] op_sel_hi:[0,1,1]
	v_pk_fma_f32 v[88:89], v[4:5], v[52:53], v[88:89]
	v_add_f32_dpp v90, v90, v90 quad_perm:[1,0,3,2] row_mask:0xf bank_mask:0xf bound_ctrl:1
	v_pk_fma_f32 v[84:85], v[76:77], v[70:71], v[80:81] op_sel_hi:[0,1,1]
	ds_read_b128 v[60:63], v110 offset:6400
	v_add_f32_dpp v90, v90, v90 quad_perm:[2,3,0,1] row_mask:0xf bank_mask:0xf bound_ctrl:1
	ds_read_b128 v[56:59], v110 offset:2304
	v_add_f32_e32 v100, v88, v89
	v_add_f32_dpp v90, v90, v90 row_half_mirror row_mask:0xf bank_mask:0xf bound_ctrl:1
	ds_read_b128 v[50:53], v110 offset:18432
	ds_read_b128 v[68:71], v110 offset:14592
	v_add_f32_dpp v92, v90, v90 row_mirror row_mask:0xf bank_mask:0xf bound_ctrl:1
	ds_read_b32 v76, v111 offset:22784
	s_waitcnt lgkmcnt(11)
	v_pk_fma_f32 v[2:3], v[92:93], v[64:65], v[82:83] op_sel_hi:[0,1,1] neg_lo:[1,0,0] neg_hi:[1,0,0]
	v_pk_fma_f32 v[4:5], v[92:93], v[66:67], v[84:85] op_sel_hi:[0,1,1] neg_lo:[1,0,0] neg_hi:[1,0,0]
	ds_read_b128 v[64:67], v110 offset:10496
	s_waitcnt lgkmcnt(11)
	v_pk_mul_f32 v[86:87], v[2:3], v[38:39]
	s_waitcnt lgkmcnt(10)
	v_pk_mul_f32 v[78:79], v[2:3], v[34:35]
	v_pk_fma_f32 v[86:87], v[4:5], v[40:41], v[86:87]
	v_pk_mul_f32 v[80:81], v[4:5], v[36:37]
	s_waitcnt lgkmcnt(9)
	v_pk_mul_f32 v[88:89], v[2:3], v[72:73]
	v_add_f32_e32 v90, v86, v87
	s_waitcnt lgkmcnt(7)
	v_pk_fma_f32 v[82:83], v[54:55], v[46:47], v[78:79] op_sel_hi:[0,1,1]
	v_pk_fma_f32 v[88:89], v[4:5], v[74:75], v[88:89]
	v_add_f32_dpp v90, v90, v90 quad_perm:[1,0,3,2] row_mask:0xf bank_mask:0xf bound_ctrl:1
	v_pk_fma_f32 v[84:85], v[54:55], v[48:49], v[80:81] op_sel_hi:[0,1,1]
	ds_read_b128 v[38:41], v110 offset:6656
	v_add_f32_dpp v90, v90, v90 quad_perm:[2,3,0,1] row_mask:0xf bank_mask:0xf bound_ctrl:1
	ds_read_b128 v[34:37], v110 offset:2560
	v_add_f32_e32 v101, v88, v89
	v_add_f32_dpp v90, v90, v90 row_half_mirror row_mask:0xf bank_mask:0xf bound_ctrl:1
	ds_read_b128 v[72:75], v110 offset:18688
	ds_read_b128 v[46:49], v110 offset:14848
	v_add_f32_dpp v92, v90, v90 row_mirror row_mask:0xf bank_mask:0xf bound_ctrl:1
	ds_read_b32 v54, v111 offset:23040
	s_waitcnt lgkmcnt(11)
	v_pk_fma_f32 v[2:3], v[92:93], v[42:43], v[82:83] op_sel_hi:[0,1,1] neg_lo:[1,0,0] neg_hi:[1,0,0]
	v_pk_fma_f32 v[4:5], v[92:93], v[44:45], v[84:85] op_sel_hi:[0,1,1] neg_lo:[1,0,0] neg_hi:[1,0,0]
	ds_read_b128 v[42:45], v110 offset:10752
	s_waitcnt lgkmcnt(11)
	v_pk_mul_f32 v[86:87], v[2:3], v[60:61]
	s_waitcnt lgkmcnt(10)
	v_pk_mul_f32 v[78:79], v[2:3], v[56:57]
	v_pk_fma_f32 v[86:87], v[4:5], v[62:63], v[86:87]
	v_pk_mul_f32 v[80:81], v[4:5], v[58:59]
	s_waitcnt lgkmcnt(9)
	v_pk_mul_f32 v[88:89], v[2:3], v[50:51]
	v_add_f32_e32 v90, v86, v87
	s_waitcnt lgkmcnt(7)
	v_pk_fma_f32 v[82:83], v[76:77], v[68:69], v[78:79] op_sel_hi:[0,1,1]
	v_pk_fma_f32 v[88:89], v[4:5], v[52:53], v[88:89]
	v_add_f32_dpp v90, v90, v90 quad_perm:[1,0,3,2] row_mask:0xf bank_mask:0xf bound_ctrl:1
	v_pk_fma_f32 v[84:85], v[76:77], v[70:71], v[80:81] op_sel_hi:[0,1,1]
	ds_read_b128 v[60:63], v110 offset:6912
	v_add_f32_dpp v90, v90, v90 quad_perm:[2,3,0,1] row_mask:0xf bank_mask:0xf bound_ctrl:1
	ds_read_b128 v[56:59], v110 offset:2816
	v_add_f32_e32 v102, v88, v89
	v_add_f32_dpp v90, v90, v90 row_half_mirror row_mask:0xf bank_mask:0xf bound_ctrl:1
	ds_read_b128 v[50:53], v110 offset:18944
	ds_read_b128 v[68:71], v110 offset:15104
	v_add_f32_dpp v92, v90, v90 row_mirror row_mask:0xf bank_mask:0xf bound_ctrl:1
	ds_read_b32 v76, v111 offset:23296
	s_waitcnt lgkmcnt(11)
	v_pk_fma_f32 v[2:3], v[92:93], v[64:65], v[82:83] op_sel_hi:[0,1,1] neg_lo:[1,0,0] neg_hi:[1,0,0]
	v_pk_fma_f32 v[4:5], v[92:93], v[66:67], v[84:85] op_sel_hi:[0,1,1] neg_lo:[1,0,0] neg_hi:[1,0,0]
	ds_read_b128 v[64:67], v110 offset:11008
	s_waitcnt lgkmcnt(11)
	v_pk_mul_f32 v[86:87], v[2:3], v[38:39]
	s_waitcnt lgkmcnt(10)
	v_pk_mul_f32 v[78:79], v[2:3], v[34:35]
	v_pk_fma_f32 v[86:87], v[4:5], v[40:41], v[86:87]
	v_pk_mul_f32 v[80:81], v[4:5], v[36:37]
	s_waitcnt lgkmcnt(9)
	v_pk_mul_f32 v[88:89], v[2:3], v[72:73]
	v_add_f32_e32 v90, v86, v87
	s_waitcnt lgkmcnt(7)
	v_pk_fma_f32 v[82:83], v[54:55], v[46:47], v[78:79] op_sel_hi:[0,1,1]
	v_pk_fma_f32 v[88:89], v[4:5], v[74:75], v[88:89]
	v_add_f32_dpp v90, v90, v90 quad_perm:[1,0,3,2] row_mask:0xf bank_mask:0xf bound_ctrl:1
	v_pk_fma_f32 v[84:85], v[54:55], v[48:49], v[80:81] op_sel_hi:[0,1,1]
	ds_read_b128 v[38:41], v110 offset:7168
	v_add_f32_dpp v90, v90, v90 quad_perm:[2,3,0,1] row_mask:0xf bank_mask:0xf bound_ctrl:1
	ds_read_b128 v[34:37], v110 offset:3072
	v_add_f32_e32 v103, v88, v89
	v_add_f32_dpp v90, v90, v90 row_half_mirror row_mask:0xf bank_mask:0xf bound_ctrl:1
	ds_read_b128 v[72:75], v110 offset:19200
	ds_read_b128 v[46:49], v110 offset:15360
	v_add_f32_dpp v92, v90, v90 row_mirror row_mask:0xf bank_mask:0xf bound_ctrl:1
	ds_read_b32 v54, v111 offset:23552
	s_waitcnt lgkmcnt(11)
	v_pk_fma_f32 v[2:3], v[92:93], v[42:43], v[82:83] op_sel_hi:[0,1,1] neg_lo:[1,0,0] neg_hi:[1,0,0]
	v_pk_fma_f32 v[4:5], v[92:93], v[44:45], v[84:85] op_sel_hi:[0,1,1] neg_lo:[1,0,0] neg_hi:[1,0,0]
	ds_read_b128 v[42:45], v110 offset:11264
	s_waitcnt lgkmcnt(11)
	v_pk_mul_f32 v[86:87], v[2:3], v[60:61]
	s_waitcnt lgkmcnt(10)
	v_pk_mul_f32 v[78:79], v[2:3], v[56:57]
	v_pk_fma_f32 v[86:87], v[4:5], v[62:63], v[86:87]
	v_pk_mul_f32 v[80:81], v[4:5], v[58:59]
	s_waitcnt lgkmcnt(9)
	v_pk_mul_f32 v[88:89], v[2:3], v[50:51]
	v_add_f32_e32 v90, v86, v87
	s_waitcnt lgkmcnt(7)
	v_pk_fma_f32 v[82:83], v[76:77], v[68:69], v[78:79] op_sel_hi:[0,1,1]
	v_pk_fma_f32 v[88:89], v[4:5], v[52:53], v[88:89]
	v_add_f32_dpp v90, v90, v90 quad_perm:[1,0,3,2] row_mask:0xf bank_mask:0xf bound_ctrl:1
	v_pk_fma_f32 v[84:85], v[76:77], v[70:71], v[80:81] op_sel_hi:[0,1,1]
	ds_read_b128 v[60:63], v110 offset:7424
	v_add_f32_dpp v90, v90, v90 quad_perm:[2,3,0,1] row_mask:0xf bank_mask:0xf bound_ctrl:1
	ds_read_b128 v[56:59], v110 offset:3328
	v_add_f32_e32 v104, v88, v89
	v_add_f32_dpp v90, v90, v90 row_half_mirror row_mask:0xf bank_mask:0xf bound_ctrl:1
	ds_read_b128 v[50:53], v110 offset:19456
	ds_read_b128 v[68:71], v110 offset:15616
	v_add_f32_dpp v92, v90, v90 row_mirror row_mask:0xf bank_mask:0xf bound_ctrl:1
	ds_read_b32 v76, v111 offset:23808
	s_waitcnt lgkmcnt(11)
	v_pk_fma_f32 v[2:3], v[92:93], v[64:65], v[82:83] op_sel_hi:[0,1,1] neg_lo:[1,0,0] neg_hi:[1,0,0]
	v_pk_fma_f32 v[4:5], v[92:93], v[66:67], v[84:85] op_sel_hi:[0,1,1] neg_lo:[1,0,0] neg_hi:[1,0,0]
	ds_read_b128 v[64:67], v110 offset:11520
	s_waitcnt lgkmcnt(11)
	v_pk_mul_f32 v[86:87], v[2:3], v[38:39]
	s_waitcnt lgkmcnt(10)
	v_pk_mul_f32 v[78:79], v[2:3], v[34:35]
	v_pk_fma_f32 v[86:87], v[4:5], v[40:41], v[86:87]
	v_pk_mul_f32 v[80:81], v[4:5], v[36:37]
	s_waitcnt lgkmcnt(9)
	v_pk_mul_f32 v[88:89], v[2:3], v[72:73]
	v_add_f32_e32 v90, v86, v87
	s_waitcnt lgkmcnt(7)
	v_pk_fma_f32 v[82:83], v[54:55], v[46:47], v[78:79] op_sel_hi:[0,1,1]
	v_pk_fma_f32 v[88:89], v[4:5], v[74:75], v[88:89]
	v_add_f32_dpp v90, v90, v90 quad_perm:[1,0,3,2] row_mask:0xf bank_mask:0xf bound_ctrl:1
	v_pk_fma_f32 v[84:85], v[54:55], v[48:49], v[80:81] op_sel_hi:[0,1,1]
	ds_read_b128 v[38:41], v110 offset:7680
	v_add_f32_dpp v90, v90, v90 quad_perm:[2,3,0,1] row_mask:0xf bank_mask:0xf bound_ctrl:1
	ds_read_b128 v[34:37], v110 offset:3584
	v_add_f32_e32 v105, v88, v89
	v_add_f32_dpp v90, v90, v90 row_half_mirror row_mask:0xf bank_mask:0xf bound_ctrl:1
	ds_read_b128 v[72:75], v110 offset:19712
	ds_read_b128 v[46:49], v110 offset:15872
	v_add_f32_dpp v92, v90, v90 row_mirror row_mask:0xf bank_mask:0xf bound_ctrl:1
	ds_read_b32 v54, v111 offset:24064
	s_waitcnt lgkmcnt(11)
	v_pk_fma_f32 v[2:3], v[92:93], v[42:43], v[82:83] op_sel_hi:[0,1,1] neg_lo:[1,0,0] neg_hi:[1,0,0]
	v_pk_fma_f32 v[4:5], v[92:93], v[44:45], v[84:85] op_sel_hi:[0,1,1] neg_lo:[1,0,0] neg_hi:[1,0,0]
	ds_read_b128 v[42:45], v110 offset:11776
	s_waitcnt lgkmcnt(11)
	v_pk_mul_f32 v[86:87], v[2:3], v[60:61]
	s_waitcnt lgkmcnt(10)
	v_pk_mul_f32 v[78:79], v[2:3], v[56:57]
	v_pk_fma_f32 v[86:87], v[4:5], v[62:63], v[86:87]
	v_pk_mul_f32 v[80:81], v[4:5], v[58:59]
	s_waitcnt lgkmcnt(9)
	v_pk_mul_f32 v[88:89], v[2:3], v[50:51]
	v_add_f32_e32 v90, v86, v87
	s_waitcnt lgkmcnt(7)
	v_pk_fma_f32 v[82:83], v[76:77], v[68:69], v[78:79] op_sel_hi:[0,1,1]
	v_pk_fma_f32 v[88:89], v[4:5], v[52:53], v[88:89]
	v_add_f32_dpp v90, v90, v90 quad_perm:[1,0,3,2] row_mask:0xf bank_mask:0xf bound_ctrl:1
	v_pk_fma_f32 v[84:85], v[76:77], v[70:71], v[80:81] op_sel_hi:[0,1,1]
	ds_read_b128 v[60:63], v110 offset:7936
	v_add_f32_dpp v90, v90, v90 quad_perm:[2,3,0,1] row_mask:0xf bank_mask:0xf bound_ctrl:1
	ds_read_b128 v[56:59], v110 offset:3840
	v_add_f32_e32 v106, v88, v89
	v_add_f32_dpp v90, v90, v90 row_half_mirror row_mask:0xf bank_mask:0xf bound_ctrl:1
	ds_read_b128 v[50:53], v110 offset:19968
	ds_read_b128 v[68:71], v110 offset:16128
	v_add_f32_dpp v92, v90, v90 row_mirror row_mask:0xf bank_mask:0xf bound_ctrl:1
	ds_read_b32 v76, v111 offset:24320
	s_cmpk_eq_i32 s33, 0x10f
	s_cbranch_scc1 .Lscan_tail_last
	s_waitcnt lgkmcnt(11)
	v_pk_fma_f32 v[2:3], v[92:93], v[64:65], v[82:83] op_sel_hi:[0,1,1] neg_lo:[1,0,0] neg_hi:[1,0,0]
	v_pk_fma_f32 v[4:5], v[92:93], v[66:67], v[84:85] op_sel_hi:[0,1,1] neg_lo:[1,0,0] neg_hi:[1,0,0]
	ds_read_b128 v[64:67], v110 offset:12032
	s_waitcnt lgkmcnt(11)
	v_pk_mul_f32 v[86:87], v[2:3], v[38:39]
	s_waitcnt lgkmcnt(10)
	v_pk_mul_f32 v[78:79], v[2:3], v[34:35]
	v_pk_fma_f32 v[86:87], v[4:5], v[40:41], v[86:87]
	v_pk_mul_f32 v[80:81], v[4:5], v[36:37]
	s_waitcnt lgkmcnt(9)
	v_pk_mul_f32 v[88:89], v[2:3], v[72:73]
	v_add_f32_e32 v90, v86, v87
	s_waitcnt lgkmcnt(7)
	v_pk_fma_f32 v[82:83], v[54:55], v[46:47], v[78:79] op_sel_hi:[0,1,1]
	v_pk_fma_f32 v[88:89], v[4:5], v[74:75], v[88:89]
	v_add_f32_dpp v90, v90, v90 quad_perm:[1,0,3,2] row_mask:0xf bank_mask:0xf bound_ctrl:1
	v_pk_fma_f32 v[84:85], v[54:55], v[48:49], v[80:81] op_sel_hi:[0,1,1]
	s_waitcnt vmcnt(0)
	v_add_f32_dpp v90, v90, v90 quad_perm:[2,3,0,1] row_mask:0xf bank_mask:0xf bound_ctrl:1
	v_pk_add_f32 v[122:123], v[26:27], -1.0 op_sel_hi:[1,0]
	v_add_f32_e32 v107, v88, v89
	v_add_f32_dpp v90, v90, v90 row_half_mirror row_mask:0xf bank_mask:0xf bound_ctrl:1
	ds_read_b128 v[72:75], v110 offset:20224
	v_pk_add_f32 v[124:125], v[28:29], -1.0 op_sel_hi:[1,0]
	v_add_f32_dpp v92, v90, v90 row_mirror row_mask:0xf bank_mask:0xf bound_ctrl:1
	v_pk_mul_f32 v[118:119], v[30:31], v[26:27]
	s_waitcnt lgkmcnt(7)
	v_pk_fma_f32 v[2:3], v[92:93], v[42:43], v[82:83] op_sel_hi:[0,1,1] neg_lo:[1,0,0] neg_hi:[1,0,0]
	v_pk_fma_f32 v[4:5], v[92:93], v[44:45], v[84:85] op_sel_hi:[0,1,1] neg_lo:[1,0,0] neg_hi:[1,0,0]
	v_pk_fma_f32 v[122:123], v[6:7], v[122:123], 1.0 op_sel_hi:[1,1,0]
	s_waitcnt lgkmcnt(6)
	v_pk_mul_f32 v[86:87], v[2:3], v[60:61]
	s_waitcnt lgkmcnt(5)
	v_pk_mul_f32 v[78:79], v[2:3], v[56:57]
	v_pk_fma_f32 v[86:87], v[4:5], v[62:63], v[86:87]
	v_pk_mul_f32 v[80:81], v[4:5], v[58:59]
	s_waitcnt lgkmcnt(4)
	v_pk_mul_f32 v[88:89], v[2:3], v[50:51]
	v_add_f32_e32 v90, v86, v87
	s_waitcnt lgkmcnt(2)
	v_pk_fma_f32 v[82:83], v[76:77], v[68:69], v[78:79] op_sel_hi:[0,1,1]
	v_pk_fma_f32 v[88:89], v[4:5], v[52:53], v[88:89]
	v_add_f32_dpp v90, v90, v90 quad_perm:[1,0,3,2] row_mask:0xf bank_mask:0xf bound_ctrl:1
	v_pk_fma_f32 v[84:85], v[76:77], v[70:71], v[80:81] op_sel_hi:[0,1,1]
	v_pk_fma_f32 v[124:125], v[8:9], v[124:125], 1.0 op_sel_hi:[1,1,0]
	v_add_f32_dpp v90, v90, v90 quad_perm:[2,3,0,1] row_mask:0xf bank_mask:0xf bound_ctrl:1
	v_pk_mul_f32 v[120:121], v[32:33], v[28:29]
	v_add_f32_e32 v108, v88, v89
	v_add_f32_dpp v90, v90, v90 row_half_mirror row_mask:0xf bank_mask:0xf bound_ctrl:1
	v_pk_mul_f32 v[122:123], v[14:15], v[122:123]
	v_pk_mul_f32 v[124:125], v[16:17], v[124:125]
	v_add_f32_dpp v92, v90, v90 row_mirror row_mask:0xf bank_mask:0xf bound_ctrl:1
	ds_write_b128 v112, v[22:25] offset:0
	ds_write_b128 v112, v[30:33] offset:4096
	s_waitcnt lgkmcnt(3)
	v_pk_fma_f32 v[2:3], v[92:93], v[64:65], v[82:83] op_sel_hi:[0,1,1] neg_lo:[1,0,0] neg_hi:[1,0,0]
	v_pk_fma_f32 v[4:5], v[92:93], v[66:67], v[84:85] op_sel_hi:[0,1,1] neg_lo:[1,0,0] neg_hi:[1,0,0]
	ds_write_b128 v112, v[10:13] offset:16384
	s_waitcnt lgkmcnt(3)
	v_pk_mul_f32 v[88:89], v[2:3], v[72:73]
	ds_write_b128 v112, v[18:21] offset:20480
	v_pk_fma_f32 v[88:89], v[4:5], v[74:75], v[88:89]
	ds_write_b128 v112, v[118:121] offset:8192
	v_add_f32_e32 v109, v88, v89
	ds_write_b128 v112, v[122:125] offset:12288
	s_waitcnt lgkmcnt(0)
	v_xor_b32_e32 v110, 0x6000, v110
	v_xor_b32_e32 v111, 0x6000, v111
	v_xor_b32_e32 v112, 0x6000, v112
	s_add_i32 s33, s33, 1
	s_barrier
	s_branch .Lscan_chunk
.Lscan_tail_last:
	s_waitcnt lgkmcnt(11)
	v_pk_fma_f32 v[2:3], v[92:93], v[64:65], v[82:83] op_sel_hi:[0,1,1] neg_lo:[1,0,0] neg_hi:[1,0,0]
	v_pk_fma_f32 v[4:5], v[92:93], v[66:67], v[84:85] op_sel_hi:[0,1,1] neg_lo:[1,0,0] neg_hi:[1,0,0]
	ds_read_b128 v[64:67], v110 offset:12032
	s_waitcnt lgkmcnt(11)
	v_pk_mul_f32 v[86:87], v[2:3], v[38:39]
	s_waitcnt lgkmcnt(10)
	v_pk_mul_f32 v[78:79], v[2:3], v[34:35]
	v_pk_fma_f32 v[86:87], v[4:5], v[40:41], v[86:87]
	v_pk_mul_f32 v[80:81], v[4:5], v[36:37]
	s_waitcnt lgkmcnt(9)
	v_pk_mul_f32 v[88:89], v[2:3], v[72:73]
	v_add_f32_e32 v90, v86, v87
	s_waitcnt lgkmcnt(7)
	v_pk_fma_f32 v[82:83], v[54:55], v[46:47], v[78:79] op_sel_hi:[0,1,1]
	v_pk_fma_f32 v[88:89], v[4:5], v[74:75], v[88:89]
	v_add_f32_dpp v90, v90, v90 quad_perm:[1,0,3,2] row_mask:0xf bank_mask:0xf bound_ctrl:1
	v_pk_fma_f32 v[84:85], v[54:55], v[48:49], v[80:81] op_sel_hi:[0,1,1]
	s_nop 0
	v_add_f32_dpp v90, v90, v90 quad_perm:[2,3,0,1] row_mask:0xf bank_mask:0xf bound_ctrl:1
	s_nop 0
	v_add_f32_e32 v107, v88, v89
	v_add_f32_dpp v90, v90, v90 row_half_mirror row_mask:0xf bank_mask:0xf bound_ctrl:1
	ds_read_b128 v[72:75], v110 offset:20224
	s_nop 0
	v_add_f32_dpp v92, v90, v90 row_mirror row_mask:0xf bank_mask:0xf bound_ctrl:1
	s_nop 0
	s_waitcnt lgkmcnt(7)
	v_pk_fma_f32 v[2:3], v[92:93], v[42:43], v[82:83] op_sel_hi:[0,1,1] neg_lo:[1,0,0] neg_hi:[1,0,0]
	v_pk_fma_f32 v[4:5], v[92:93], v[44:45], v[84:85] op_sel_hi:[0,1,1] neg_lo:[1,0,0] neg_hi:[1,0,0]
	s_nop 0
	s_waitcnt lgkmcnt(6)
	v_pk_mul_f32 v[86:87], v[2:3], v[60:61]
	s_waitcnt lgkmcnt(5)
	v_pk_mul_f32 v[78:79], v[2:3], v[56:57]
	v_pk_fma_f32 v[86:87], v[4:5], v[62:63], v[86:87]
	v_pk_mul_f32 v[80:81], v[4:5], v[58:59]
	s_waitcnt lgkmcnt(4)
	v_pk_mul_f32 v[88:89], v[2:3], v[50:51]
	v_add_f32_e32 v90, v86, v87
	s_waitcnt lgkmcnt(2)
	v_pk_fma_f32 v[82:83], v[76:77], v[68:69], v[78:79] op_sel_hi:[0,1,1]
	v_pk_fma_f32 v[88:89], v[4:5], v[52:53], v[88:89]
	v_add_f32_dpp v90, v90, v90 quad_perm:[1,0,3,2] row_mask:0xf bank_mask:0xf bound_ctrl:1
	v_pk_fma_f32 v[84:85], v[76:77], v[70:71], v[80:81] op_sel_hi:[0,1,1]
	s_nop 0
	v_add_f32_dpp v90, v90, v90 quad_perm:[2,3,0,1] row_mask:0xf bank_mask:0xf bound_ctrl:1
	s_nop 0
	v_add_f32_e32 v108, v88, v89
	v_add_f32_dpp v90, v90, v90 row_half_mirror row_mask:0xf bank_mask:0xf bound_ctrl:1
	s_nop 0
	s_nop 0
	v_add_f32_dpp v92, v90, v90 row_mirror row_mask:0xf bank_mask:0xf bound_ctrl:1
	s_nop 0
	s_waitcnt lgkmcnt(1)
	v_pk_fma_f32 v[2:3], v[92:93], v[64:65], v[82:83] op_sel_hi:[0,1,1] neg_lo:[1,0,0] neg_hi:[1,0,0]
	v_pk_fma_f32 v[4:5], v[92:93], v[66:67], v[84:85] op_sel_hi:[0,1,1] neg_lo:[1,0,0] neg_hi:[1,0,0]
	s_nop 0
	s_waitcnt lgkmcnt(0)
	v_pk_mul_f32 v[88:89], v[2:3], v[72:73]
	s_nop 0
	v_pk_fma_f32 v[88:89], v[4:5], v[74:75], v[88:89]
	s_nop 0
	v_add_f32_e32 v109, v88, v89
	v_cndmask_b32_e64 v118, v102, v94, s[38:39]
	v_cndmask_b32_e64 v119, v103, v95, s[38:39]
	v_cndmask_b32_e64 v120, v104, v96, s[38:39]
	v_cndmask_b32_e64 v121, v105, v97, s[38:39]
	v_cndmask_b32_e64 v122, v106, v98, s[38:39]
	v_cndmask_b32_e64 v123, v107, v99, s[38:39]
	v_cndmask_b32_e64 v124, v108, v100, s[38:39]
	v_cndmask_b32_e64 v125, v109, v101, s[38:39]
	v_cndmask_b32_e64 v94, v94, v102, s[38:39]
	v_cndmask_b32_e64 v95, v95, v103, s[38:39]
	v_cndmask_b32_e64 v96, v96, v104, s[38:39]
	v_cndmask_b32_e64 v97, v97, v105, s[38:39]
	v_cndmask_b32_e64 v98, v98, v106, s[38:39]
	v_cndmask_b32_e64 v99, v99, v107, s[38:39]
	v_cndmask_b32_e64 v100, v100, v108, s[38:39]
	v_cndmask_b32_e64 v101, v101, v109, s[38:39]
	v_add_f32_dpp v94, v118, v94 row_ror:8 row_mask:0xf bank_mask:0xf bound_ctrl:1
	v_add_f32_dpp v95, v119, v95 row_ror:8 row_mask:0xf bank_mask:0xf bound_ctrl:1
	v_add_f32_dpp v96, v120, v96 row_ror:8 row_mask:0xf bank_mask:0xf bound_ctrl:1
	v_add_f32_dpp v97, v121, v97 row_ror:8 row_mask:0xf bank_mask:0xf bound_ctrl:1
	v_add_f32_dpp v98, v122, v98 row_ror:8 row_mask:0xf bank_mask:0xf bound_ctrl:1
	v_add_f32_dpp v99, v123, v99 row_ror:8 row_mask:0xf bank_mask:0xf bound_ctrl:1
	v_add_f32_dpp v100, v124, v100 row_ror:8 row_mask:0xf bank_mask:0xf bound_ctrl:1
	v_add_f32_dpp v101, v125, v101 row_ror:8 row_mask:0xf bank_mask:0xf bound_ctrl:1
	v_cndmask_b32_e64 v118, v98, v94, s[40:41]
	v_cndmask_b32_e64 v119, v99, v95, s[40:41]
	v_cndmask_b32_e64 v120, v100, v96, s[40:41]
	v_cndmask_b32_e64 v121, v101, v97, s[40:41]
	v_cndmask_b32_e64 v94, v94, v98, s[40:41]
	v_cndmask_b32_e64 v95, v95, v99, s[40:41]
	v_cndmask_b32_e64 v96, v96, v100, s[40:41]
	v_cndmask_b32_e64 v97, v97, v101, s[40:41]
	v_add_f32_dpp v94, v118, v94 row_half_mirror row_mask:0xf bank_mask:0xf bound_ctrl:1
	v_add_f32_dpp v95, v119, v95 row_half_mirror row_mask:0xf bank_mask:0xf bound_ctrl:1
	v_add_f32_dpp v96, v120, v96 row_half_mirror row_mask:0xf bank_mask:0xf bound_ctrl:1
	v_add_f32_dpp v97, v121, v97 row_half_mirror row_mask:0xf bank_mask:0xf bound_ctrl:1
	v_cndmask_b32_e64 v118, v96, v94, s[42:43]
	v_cndmask_b32_e64 v119, v97, v95, s[42:43]
	v_cndmask_b32_e64 v94, v94, v96, s[42:43]
	v_cndmask_b32_e64 v95, v95, v97, s[42:43]
	s_nop 0
	v_add_f32_dpp v94, v118, v94 quad_perm:[1,0,3,2] row_mask:0xf bank_mask:0xf bound_ctrl:1
	v_add_f32_dpp v95, v119, v95 quad_perm:[1,0,3,2] row_mask:0xf bank_mask:0xf bound_ctrl:1
	s_nop 0
	v_cndmask_b32_e64 v118, v95, v94, s[44:45]
	v_cndmask_b32_e64 v94, v94, v95, s[44:45]
	s_nop 1
	v_add_f32_dpp v94, v118, v94 quad_perm:[2,3,0,1] row_mask:0xf bank_mask:0xf bound_ctrl:1
	v_lshl_add_u32 v0, v114, 10, v116
	v_add_u32_e32 v114, s34, v114
	global_store_dword v0, v94, s[50:51]
	s_barrier
	s_setprio 0
	v_readlane_b32 s42, v208, 51
	v_readlane_b32 s54, v209, 14
	v_readlane_b32 s43, v208, 52
	v_readlane_b32 s55, v209, 15
	v_readlane_b32 s69, v208, 57
	s_movk_i32 s53, 0x2000
	s_mov_b32 s52, 0xb000
